# grid barrier: non-leader workgroups issue their acquire invalidate (buffer_inv sc1) right after arriving, overlapped with the wait for the release, instead of after it
# speedup vs baseline: 1.0872x; 1.0075x over previous
.LBB0_821:
	s_or_b64 exec, exec, s[6:7]
	v_cvt_f32_u32_e32 v5, v3
	s_waitcnt vmcnt(0)
	v_readfirstlane_b32 s4, v4
	v_sub_u32_e32 v4, 0, v3
	v_rcp_iflag_f32_e32 v5, v5
	v_add_u32_e32 v6, s4, v0
	v_mul_f32_e32 v5, 0x4f7ffffe, v5
	v_cvt_u32_f32_e32 v5, v5
	v_mul_lo_u32 v0, v4, v5
	v_mul_hi_u32 v0, v5, v0
	v_add_u32_e32 v0, v5, v0
	v_mul_hi_u32 v0, v6, v0
	v_mul_lo_u32 v4, v0, v3
	v_sub_u32_e32 v4, v6, v4
	v_add_u32_e32 v5, 1, v0
	v_cmp_ge_u32_e32 vcc, v4, v3
	s_nop 1
	v_cndmask_b32_e32 v0, v0, v5, vcc
	v_sub_u32_e32 v5, v4, v3
	v_cndmask_b32_e32 v4, v4, v5, vcc
	v_add_u32_e32 v5, 1, v0
	v_cmp_ge_u32_e32 vcc, v4, v3
	v_add_u32_e32 v4, 1, v6
	s_nop 0
	v_cndmask_b32_e32 v0, v0, v5, vcc
	v_mul_lo_u32 v5, v3, v0
	v_add_u32_e32 v3, v5, v3
	v_cmp_ne_u32_e32 vcc, v4, v3
	s_and_saveexec_b64 s[4:5], vcc
	s_xor_b64 s[6:7], exec, s[4:5]
	s_cbranch_execz .LBB0_835
	buffer_inv sc1
	v_readlane_b32 s4, v254, 43
	v_readlane_b32 s5, v254, 44
	s_waitcnt lgkmcnt(0)
	s_nop 3
	global_load_dword v2, v1, s[4:5] sc1
	s_waitcnt vmcnt(0)
	v_cmp_eq_u32_e32 vcc, v2, v0
	s_and_saveexec_b64 s[14:15], vcc
	s_cbranch_execz .LBB0_834
	s_mov_b32 s4, 1
	s_mov_b64 s[16:17], 0
	s_branch .LBB0_825

.LBB0_834:
	s_or_b64 exec, exec, s[14:15]
	s_waitcnt vmcnt(0)
.LBB0_835:
	s_andn2_saveexec_b64 s[4:5], s[6:7]
	s_cbranch_execnz .LBB0_836
	s_getpc_b64 s[98:99]
